# MoBA K workspace also in MFMA-fragment order (REG3 epilogue k stores + S-wave K loads coalesced to full lines)
# speedup vs baseline: 1.0817x; 1.0045x over previous
; DI u32x2 pk4(f32x4 v) { u32x2 r; r.x = pk2(v[0], v[1]); r.y = pk2(v[2], v[3]); return r; }
; template <int REG>
; DI void epi_inproj(const Params& p, f32x4 (&acc)[2][2][4][2], int pm, int pn, LAS unsigned char* shm) {
;     ...
;     const bool isk = pn >= 14;
;     const float* nw = isk ? p.k_norm_w : p.q_norm_w;
;     bf16_t* dstb = (bf16_t*)(ws + (isk ? OFF_MK : OFF_MQ));
;     const int hh = (pn & 1) * 4 + wc;
;     f32x4 w4[2][2], cs4[2][2];
; #pragma unroll
;     for (int bj = 0; bj < 2; ++bj)
; #pragma unroll
;       for (int n = 0; n < 2; ++n) { w4[bj][n] = *(const f32x4*)(nw + 32 * bj + 8 * fq + 4 * n); cs4[bj][n] = (f32x4){0.f, 0.f, 0.f, 0.f}; }
; #pragma unroll
;     for (int ai = 0; ai < 2; ++ai)
; #pragma unroll
;       for (int m = 0; m < 4; ++m) { asm volatile("" ::: "memory");
;         const int r = 128 * ai + 64 * wr + 16 * m + fr, t = t0 + r;
;         const float rs = rsr[ai][m];
;         f32x4 v[2][2]; float ss = 0.f;
; #pragma unroll
;         for (int bj = 0; bj < 2; ++bj)
; #pragma unroll
;           for (int n = 0; n < 2; ++n) { v[bj][n] = acc[ai][bj][m][n] * rs; ss += v[bj][n][0] * v[bj][n][0] + v[bj][n][1] * v[bj][n][1] + v[bj][n][2] * v[bj][n][2] + v[bj][n][3] * v[bj][n][3]; }
;         ss += __shfl_xor(ss, 16); ss += __shfl_xor(ss, 32);
;         const float rn = __builtin_amdgcn_rsqf(ss * (1.0f / 64.0f) + 1e-6f) * (isk ? 1.0f : 0.125f * 1.4426950408889634f);
;         bf16_t* dst = dstb + ((long)((b * 8 + hh) * SEQ + t)) * 64 + 8 * fq;
; #pragma unroll
;         for (int bj = 0; bj < 2; ++bj) {
;           const f32x4 o0 = v[bj][0] * rn * w4[bj][0], o1 = v[bj][1] * rn * w4[bj][1]; cs4[bj][0] += o0; cs4[bj][1] += o1;
;           const u32x2 h0 = pk4(o0), h1 = pk4(o1);
;           *(u32x4*)(dst + 32 * bj) = (u32x4){h0.x, h0.y, h1.x, h1.y};
.LBB0_435:
	v_mov_b32_e32 v168, v194
	s_lshl_b32 s48, s22, 8
	s_ashr_i32 s49, s48, 31
	v_and_b32_e32 v170, 15, v168
	s_and_b32 s46, s22, 31
	v_ashrrev_i32_e32 v175, 8, v168
	s_lshl_b64 s[48:49], s[48:49], 2
	v_lshlrev_b32_e32 v112, 3, v170
	s_add_u32 s48, s65, s48
	v_lshl_or_b32 v112, v175, 7, v112
	s_addc_u32 s49, s67, s49
	v_ashrrev_i32_e32 v113, 31, v112
	v_lshl_add_u64 v[112:113], v[112:113], 2, s[48:49]
	global_load_dwordx4 v[148:151], v[112:113], off
	s_nop 0
	global_load_dwordx4 v[112:115], v[112:113], off offset:16
	s_lshl_b32 s23, s40, 2
	s_cmp_gt_i32 s40, 13
	s_cselect_b64 s[48:49], -1, 0
	v_bfe_u32 v118, v168, 4, 2
	v_cndmask_b32_e64 v174, v167, 1.0, s[48:49]
	s_and_b64 s[48:49], s[48:49], exec
	v_lshlrev_b32_e32 v171, 5, v118
	s_cselect_b32 s48, s44, s42
	s_cselect_b32 s49, s45, s43
	global_load_dwordx4 v[124:127], v171, s[48:49] offset:16
	global_load_dwordx4 v[132:135], v171, s[48:49]
	v_and_b32_e32 v117, 64, v165
	v_xor_b32_e32 v116, 16, v165
	v_add_u32_e32 v172, 64, v117
	v_cmp_lt_i32_e32 vcc, v116, v172
	v_xor_b32_e32 v173, 32, v165
	v_lshlrev_b32_e32 v195, 6, v175
	v_cndmask_b32_e32 v176, v165, v116, vcc
	global_load_dwordx4 v[116:119], v171, s[48:49] offset:144
	global_load_dwordx4 v[128:131], v171, s[48:49] offset:128
	v_lshlrev_b32_e32 v176, 2, v176
	v_cmp_lt_i32_e32 vcc, v173, v172
	s_cselect_b32 s47, s76, 0x10300000
	s_add_u32 s48, s26, s47
	v_cndmask_b32_e32 v177, v165, v173, vcc
	v_lshlrev_b32_e32 v175, 2, v177
	s_addc_u32 s49, s27, 0
	s_ashr_i32 s22, s22, 2
	v_ashrrev_i32_e32 v169, 6, v168
	s_and_b32 s23, s23, 4
	s_and_b32 s22, s22, -8
	v_and_b32_e32 v173, 3, v169
	s_or_b32 s47, s22, s23
	v_lshl_or_b32 v196, s46, 8, v170
	v_and_b32_e32 v156, 48, v168
	s_cmp_gt_i32 s40, 13
	s_cselect_b32 s100, 0x3c0, 0
	s_mov_b32 s101, 0
	s_cselect_b64 s[98:99], -1, 0
	v_bfe_u32 v238, v170, 2, 1
	v_mul_u32_u24_e32 v238, 0x600, v238
	v_mad_u32_u24 v238, v156, 15, v238
	v_lshrrev_b32_e32 v240, 3, v170
	v_mul_u32_u24_e32 v240, 0x3c0, v240
	v_sub_u32_e32 v238, v238, v240
	v_and_b32_e32 v240, 3, v170
	v_mul_u32_u24_e32 v240, 0x70, v240
	v_sub_u32_e32 v238, v238, v240
	v_add_u32_e32 v240, 0xfffff880, v238
	v_cndmask_b32_e64 v238, 0, v238, s[98:99]
	v_cndmask_b32_e64 v240, 0, v240, s[98:99]
	v_ashrrev_i32_e32 v239, 31, v238
	v_ashrrev_i32_e32 v241, 31, v240
	s_cmp_lt_i32 s40, 14
	s_waitcnt vmcnt(0)
	v_pk_mul_f32 v[178:179], v[144:145], v[148:149] op_sel_hi:[1,0]
	v_pk_mul_f32 v[140:141], v[140:141], v[148:149] op_sel_hi:[1,0]
	v_pk_mul_f32 v[136:137], v[136:137], v[148:149] op_sel_hi:[1,0]
	v_pk_mul_f32 v[182:183], v[122:123], v[148:149] op_sel_hi:[1,0]
	v_pk_mul_f32 v[184:185], v[120:121], v[148:149] op_sel_hi:[1,0]
	v_mov_b32_e32 v122, v179
	v_mov_b32_e32 v123, v141
	v_pk_mul_f32 v[146:147], v[146:147], v[148:149] op_sel_hi:[1,0]
	v_pk_mul_f32 v[180:181], v[142:143], v[148:149] op_sel_hi:[1,0]
	v_mov_b32_e32 v120, v178
	v_mov_b32_e32 v121, v140
	v_mov_b32_e32 v188, v185
	v_mov_b32_e32 v189, v137
	v_pk_mul_f32 v[122:123], v[122:123], v[122:123]
	v_pk_mul_f32 v[138:139], v[138:139], v[148:149] op_sel_hi:[1,0]
	v_mov_b32_e32 v142, v146
	v_mov_b32_e32 v143, v180
	v_mov_b32_e32 v186, v184
	v_mov_b32_e32 v187, v136
	v_pk_mul_f32 v[188:189], v[188:189], v[188:189]
	v_pk_fma_f32 v[120:121], v[120:121], v[120:121], v[122:123]
	v_mov_b32_e32 v144, v147
	v_mov_b32_e32 v145, v181
	v_mov_b32_e32 v190, v182
	v_mov_b32_e32 v191, v138
	v_pk_fma_f32 v[122:123], v[186:187], v[186:187], v[188:189]
	v_pk_fma_f32 v[120:121], v[142:143], v[142:143], v[120:121]
	v_mov_b32_e32 v192, v183
	v_mov_b32_e32 v193, v139
	v_pk_fma_f32 v[122:123], v[190:191], v[190:191], v[122:123]
	v_pk_fma_f32 v[120:121], v[144:145], v[144:145], v[120:121]
	v_pk_fma_f32 v[122:123], v[192:193], v[192:193], v[122:123]
	v_add_f32_e32 v120, v120, v121
	v_add_f32_e32 v120, v123, v120
	v_add_f32_e32 v120, v122, v120
	ds_bpermute_b32 v121, v176, v120
	v_or_b32_e32 v122, s47, v173
	v_lshlrev_b32_e32 v122, 13, v122
	v_add3_u32 v144, v196, v195, v122
	v_ashrrev_i32_e32 v145, 31, v144
	s_waitcnt lgkmcnt(0)
	v_add_f32_e32 v120, v120, v121
	ds_bpermute_b32 v121, v175, v120
	v_lshl_add_u64 v[142:143], s[48:49], 0, v[156:157]
	v_pk_mul_f32 v[108:109], v[108:109], v[148:149] op_sel:[0,1]
	v_pk_mul_f32 v[100:101], v[100:101], v[148:149] op_sel:[0,1]
	v_pk_mul_f32 v[192:193], v[96:97], v[148:149] op_sel:[0,1]
	s_waitcnt lgkmcnt(0)
; DI u32x2 pk4(f32x4 v) { u32x2 r; r.x = pk2(v[0], v[1]); r.y = pk2(v[2], v[3]); return r; }
; template <int REG>
; DI void epi_inproj(const Params& p, f32x4 (&acc)[2][2][4][2], int pm, int pn, LAS unsigned char* shm) {
;     ...
;         const int r = 128 * ai + 64 * wr + 16 * m + fr, t = t0 + r;
;         const float rs = rsr[ai][m];
;         f32x4 v[2][2]; float ss = 0.f;
; #pragma unroll
;         for (int bj = 0; bj < 2; ++bj)
; #pragma unroll
;           for (int n = 0; n < 2; ++n) { v[bj][n] = acc[ai][bj][m][n] * rs; ss += v[bj][n][0] * v[bj][n][0] + v[bj][n][1] * v[bj][n][1] + v[bj][n][2] * v[bj][n][2] + v[bj][n][3] * v[bj][n][3]; }
;         ss += __shfl_xor(ss, 16); ss += __shfl_xor(ss, 32);
;         const float rn = __builtin_amdgcn_rsqf(ss * (1.0f / 64.0f) + 1e-6f) * (isk ? 1.0f : 0.125f * 1.4426950408889634f);
;         bf16_t* dst = dstb + ((long)((b * 8 + hh) * SEQ + t)) * 64 + 8 * fq;
; #pragma unroll
;         for (int bj = 0; bj < 2; ++bj) {
;           const f32x4 o0 = v[bj][0] * rn * w4[bj][0], o1 = v[bj][1] * rn * w4[bj][1]; cs4[bj][0] += o0; cs4[bj][1] += o1;
;           const u32x2 h0 = pk4(o0), h1 = pk4(o1);
;           *(u32x4*)(dst + 32 * bj) = (u32x4){h0.x, h0.y, h1.x, h1.y};
;         }
	v_add_f32_e32 v120, v120, v121
	v_fmamk_f32 v120, v120, 0x3c800000, v166
	v_rsq_f32_e32 v122, v120
	v_lshlrev_b64 v[120:121], 7, v[144:145]
	v_lshl_add_u64 v[186:187], v[142:143], 0, v[120:121]
	v_lshl_add_u64 v[186:187], v[186:187], 0, v[238:239]
	v_pk_mul_f32 v[110:111], v[110:111], v[148:149] op_sel:[0,1]
	v_mul_f32_e32 v156, v174, v122
	v_pk_mul_f32 v[120:121], v[178:179], v[156:157] op_sel_hi:[1,0]
	v_pk_mul_f32 v[122:123], v[146:147], v[156:157] op_sel_hi:[1,0]
	v_pk_mul_f32 v[146:147], v[140:141], v[156:157] op_sel_hi:[1,0]
	v_pk_mul_f32 v[178:179], v[180:181], v[156:157] op_sel_hi:[1,0]
	v_pk_mul_f32 v[188:189], v[136:137], v[156:157] op_sel_hi:[1,0]
	v_pk_mul_f32 v[190:191], v[138:139], v[156:157] op_sel_hi:[1,0]
	v_pk_mul_f32 v[138:139], v[134:135], v[122:123]
	v_pk_mul_f32 v[140:141], v[132:133], v[120:121]
	v_pk_mul_f32 v[122:123], v[126:127], v[178:179]
	v_pk_mul_f32 v[136:137], v[124:125], v[146:147]
	v_cvt_pk_bf16_f32 v178, v140, v141
	v_cvt_pk_bf16_f32 v179, v138, v139
	v_cvt_pk_bf16_f32 v180, v136, v137
	v_cvt_pk_bf16_f32 v181, v122, v123
	global_store_dwordx4 v[186:187], v[178:181], off
	v_pk_mul_f32 v[146:147], v[106:107], v[148:149] op_sel:[0,1]
	v_mov_b32_e32 v106, v109
	v_pk_mul_f32 v[178:179], v[104:105], v[148:149] op_sel:[0,1]
	v_pk_mul_f32 v[120:121], v[130:131], v[190:191]
	v_mov_b32_e32 v107, v179
	v_mov_b32_e32 v104, v108
	v_mov_b32_e32 v105, v178
	v_pk_mul_f32 v[106:107], v[106:107], v[106:107]
	v_pk_mul_f32 v[190:191], v[98:99], v[148:149] op_sel:[0,1]
	v_mov_b32_e32 v98, v193
	v_mov_b32_e32 v99, v101
	v_pk_fma_f32 v[104:105], v[104:105], v[104:105], v[106:107]
	v_mov_b32_e32 v106, v110
	v_mov_b32_e32 v107, v146
	v_pk_mul_f32 v[180:181], v[102:103], v[148:149] op_sel:[0,1]
	v_mov_b32_e32 v96, v192
	v_mov_b32_e32 v97, v100
	v_pk_mul_f32 v[98:99], v[98:99], v[98:99]
	v_pk_fma_f32 v[104:105], v[106:107], v[106:107], v[104:105]
	v_mov_b32_e32 v106, v111
	v_mov_b32_e32 v107, v147
	v_pk_fma_f32 v[96:97], v[96:97], v[96:97], v[98:99]
	v_mov_b32_e32 v98, v190
	v_mov_b32_e32 v99, v180
	v_pk_fma_f32 v[104:105], v[106:107], v[106:107], v[104:105]
	v_pk_fma_f32 v[96:97], v[98:99], v[98:99], v[96:97]
	v_mov_b32_e32 v98, v191
	v_mov_b32_e32 v99, v181
	v_pk_fma_f32 v[96:97], v[98:99], v[98:99], v[96:97]
	v_add_f32_e32 v98, v104, v105
	v_add_f32_e32 v97, v97, v98
	v_add_f32_e32 v104, v96, v97
	ds_bpermute_b32 v105, v176, v104
	v_pk_mul_f32 v[98:99], v[184:185], v[156:157] op_sel_hi:[1,0]
	v_pk_mul_f32 v[96:97], v[182:183], v[156:157] op_sel_hi:[1,0]
	v_pk_mul_f32 v[102:103], v[128:129], v[188:189]
	v_pk_mul_f32 v[96:97], v[118:119], v[96:97]
	s_waitcnt lgkmcnt(0)
	v_add_f32_e32 v107, v104, v105
	ds_bpermute_b32 v145, v175, v107
	v_pk_mul_f32 v[98:99], v[116:117], v[98:99]
	v_cvt_pk_bf16_f32 v104, v102, v103
	v_cvt_pk_bf16_f32 v105, v120, v121
	v_cvt_pk_bf16_f32 v106, v98, v99
	s_waitcnt lgkmcnt(0)
	v_add_f32_e32 v107, v107, v145
	v_fmamk_f32 v107, v107, 0x3c800000, v166
	v_rsq_f32_e32 v145, v107
	v_cvt_pk_bf16_f32 v107, v96, v97
	v_lshl_add_u64 v[186:187], v[186:187], 0, s[100:101]
	global_store_dwordx4 v[186:187], v[104:107], off offset:64
	v_pk_mul_f32 v[92:93], v[92:93], v[150:151] op_sel_hi:[1,0]
	v_mul_f32_e32 v156, v174, v145
	v_or_b32_e32 v104, 16, v144
	v_ashrrev_i32_e32 v105, 31, v104
	v_lshlrev_b64 v[104:105], 7, v[104:105]
	v_lshl_add_u64 v[182:183], v[142:143], 0, v[104:105]
	v_lshl_add_u64 v[182:183], v[182:183], 0, v[240:241]
	v_pk_mul_f32 v[104:105], v[108:109], v[156:157] op_sel_hi:[1,0]
	v_pk_mul_f32 v[106:107], v[110:111], v[156:157] op_sel_hi:[1,0]
	v_pk_mul_f32 v[110:111], v[132:133], v[104:105]
	v_pk_mul_f32 v[108:109], v[134:135], v[106:107]
	v_pk_mul_f32 v[106:107], v[178:179], v[156:157] op_sel_hi:[1,0]
	v_pk_mul_f32 v[104:105], v[146:147], v[156:157] op_sel_hi:[1,0]
	v_pk_mul_f32 v[106:107], v[124:125], v[106:107]
	v_pk_mul_f32 v[104:105], v[126:127], v[104:105]
	v_cvt_pk_bf16_f32 v146, v110, v111
	v_cvt_pk_bf16_f32 v147, v108, v109
	v_cvt_pk_bf16_f32 v148, v106, v107
	v_cvt_pk_bf16_f32 v149, v104, v105
	v_pk_mul_f32 v[178:179], v[88:89], v[150:151] op_sel_hi:[1,0]
	global_store_dwordx4 v[182:183], v[146:149], off
	v_pk_mul_f32 v[84:85], v[84:85], v[150:151] op_sel_hi:[1,0]
	v_pk_mul_f32 v[186:187], v[80:81], v[150:151] op_sel_hi:[1,0]
	v_pk_mul_f32 v[148:149], v[90:91], v[150:151] op_sel_hi:[1,0]
	v_mov_b32_e32 v90, v93
	v_mov_b32_e32 v91, v179
	v_pk_mul_f32 v[94:95], v[94:95], v[150:151] op_sel_hi:[1,0]
	v_mov_b32_e32 v88, v92
	v_mov_b32_e32 v89, v178
	v_pk_mul_f32 v[90:91], v[90:91], v[90:91]
	v_pk_mul_f32 v[184:185], v[82:83], v[150:151] op_sel_hi:[1,0]
	v_mov_b32_e32 v82, v187
	v_mov_b32_e32 v83, v85
	v_pk_mul_f32 v[146:147], v[100:101], v[156:157] op_sel_hi:[1,0]
	v_pk_mul_f32 v[100:101], v[180:181], v[156:157] op_sel_hi:[1,0]
	v_pk_fma_f32 v[88:89], v[88:89], v[88:89], v[90:91]
	v_mov_b32_e32 v90, v94
	v_mov_b32_e32 v91, v148
	v_pk_mul_f32 v[180:181], v[86:87], v[150:151] op_sel_hi:[1,0]
	v_mov_b32_e32 v80, v186
	v_mov_b32_e32 v81, v84
	v_pk_mul_f32 v[82:83], v[82:83], v[82:83]
	v_pk_fma_f32 v[88:89], v[90:91], v[90:91], v[88:89]
	v_mov_b32_e32 v90, v95
	v_mov_b32_e32 v91, v149
	v_pk_fma_f32 v[80:81], v[80:81], v[80:81], v[82:83]
	v_mov_b32_e32 v82, v184
	v_mov_b32_e32 v83, v180
	v_pk_fma_f32 v[88:89], v[90:91], v[90:91], v[88:89]
	v_pk_fma_f32 v[80:81], v[82:83], v[82:83], v[80:81]
	v_mov_b32_e32 v82, v185
	v_mov_b32_e32 v83, v181
	v_pk_fma_f32 v[80:81], v[82:83], v[82:83], v[80:81]
	v_add_f32_e32 v82, v88, v89
	v_add_f32_e32 v81, v81, v82
	v_add_f32_e32 v88, v80, v81
	ds_bpermute_b32 v89, v176, v88
	v_pk_mul_f32 v[82:83], v[192:193], v[156:157] op_sel_hi:[1,0]
	v_pk_mul_f32 v[80:81], v[190:191], v[156:157] op_sel_hi:[1,0]
	v_pk_mul_f32 v[100:101], v[130:131], v[100:101]
	v_pk_mul_f32 v[86:87], v[128:129], v[146:147]
	s_waitcnt lgkmcnt(0)
; DI u32x2 pk4(f32x4 v) { u32x2 r; r.x = pk2(v[0], v[1]); r.y = pk2(v[2], v[3]); return r; }
; template <int REG>
; DI void epi_inproj(const Params& p, f32x4 (&acc)[2][2][4][2], int pm, int pn, LAS unsigned char* shm) {
;     ...
;         const int r = 128 * ai + 64 * wr + 16 * m + fr, t = t0 + r;
;         const float rs = rsr[ai][m];
;         f32x4 v[2][2]; float ss = 0.f;
; #pragma unroll
;         for (int bj = 0; bj < 2; ++bj)
; #pragma unroll
;           for (int n = 0; n < 2; ++n) { v[bj][n] = acc[ai][bj][m][n] * rs; ss += v[bj][n][0] * v[bj][n][0] + v[bj][n][1] * v[bj][n][1] + v[bj][n][2] * v[bj][n][2] + v[bj][n][3] * v[bj][n][3]; }
;         ss += __shfl_xor(ss, 16); ss += __shfl_xor(ss, 32);
;         const float rn = __builtin_amdgcn_rsqf(ss * (1.0f / 64.0f) + 1e-6f) * (isk ? 1.0f : 0.125f * 1.4426950408889634f);
;         bf16_t* dst = dstb + ((long)((b * 8 + hh) * SEQ + t)) * 64 + 8 * fq;
; #pragma unroll
;         for (int bj = 0; bj < 2; ++bj) {
;           const f32x4 o0 = v[bj][0] * rn * w4[bj][0], o1 = v[bj][1] * rn * w4[bj][1]; cs4[bj][0] += o0; cs4[bj][1] += o1;
;           const u32x2 h0 = pk4(o0), h1 = pk4(o1);
;           *(u32x4*)(dst + 32 * bj) = (u32x4){h0.x, h0.y, h1.x, h1.y};
;         }
	v_add_f32_e32 v91, v88, v89
	ds_bpermute_b32 v145, v175, v91
	v_pk_mul_f32 v[80:81], v[118:119], v[80:81]
	v_pk_mul_f32 v[82:83], v[116:117], v[82:83]
	v_cvt_pk_bf16_f32 v88, v86, v87
	v_cvt_pk_bf16_f32 v89, v100, v101
	s_waitcnt lgkmcnt(0)
	v_add_f32_e32 v91, v91, v145
	v_fmamk_f32 v91, v91, 0x3c800000, v166
	v_rsq_f32_e32 v145, v91
	v_cvt_pk_bf16_f32 v90, v82, v83
	v_cvt_pk_bf16_f32 v91, v80, v81
	v_lshl_add_u64 v[182:183], v[182:183], 0, s[100:101]
	global_store_dwordx4 v[182:183], v[88:91], off offset:64
	v_mul_f32_e32 v150, v174, v145
	v_pk_mul_f32 v[60:61], v[60:61], v[112:113] op_sel_hi:[1,0]
	v_or_b32_e32 v88, 32, v144
	v_ashrrev_i32_e32 v89, 31, v88
	v_lshlrev_b64 v[88:89], 7, v[88:89]
	v_lshl_add_u64 v[182:183], v[142:143], 0, v[88:89]
	v_lshl_add_u64 v[182:183], v[182:183], 0, v[238:239]
	v_pk_mul_f32 v[88:89], v[92:93], v[150:151] op_sel_hi:[1,0]
	v_pk_mul_f32 v[90:91], v[94:95], v[150:151] op_sel_hi:[1,0]
	v_pk_mul_f32 v[94:95], v[132:133], v[88:89]
	v_pk_mul_f32 v[92:93], v[134:135], v[90:91]
	v_pk_mul_f32 v[90:91], v[178:179], v[150:151] op_sel_hi:[1,0]
	v_pk_mul_f32 v[88:89], v[148:149], v[150:151] op_sel_hi:[1,0]
	v_pk_mul_f32 v[90:91], v[124:125], v[90:91]
	v_pk_mul_f32 v[88:89], v[126:127], v[88:89]
	v_cvt_pk_bf16_f32 v146, v94, v95
	v_cvt_pk_bf16_f32 v147, v92, v93
	v_cvt_pk_bf16_f32 v148, v90, v91
	v_cvt_pk_bf16_f32 v149, v88, v89
	global_store_dwordx4 v[182:183], v[146:149], off
	v_pk_mul_f32 v[56:57], v[56:57], v[112:113] op_sel_hi:[1,0]
	v_pk_mul_f32 v[62:63], v[62:63], v[112:113] op_sel_hi:[1,0]
	v_mov_b32_e32 v148, v151
	v_pk_mul_f32 v[146:147], v[84:85], v[150:151] op_sel_hi:[1,0]
	v_pk_mul_f32 v[84:85], v[180:181], v[150:151] op_sel_hi:[1,0]
	v_pk_mul_f32 v[76:77], v[76:77], v[148:149] op_sel_hi:[1,0]
	v_pk_mul_f32 v[180:181], v[72:73], v[148:149] op_sel_hi:[1,0]
	v_pk_mul_f32 v[178:179], v[74:75], v[148:149] op_sel_hi:[1,0]
	v_mov_b32_e32 v74, v77
	v_mov_b32_e32 v75, v181
	v_pk_mul_f32 v[68:69], v[68:69], v[148:149] op_sel_hi:[1,0]
	v_pk_mul_f32 v[192:193], v[64:65], v[148:149] op_sel_hi:[1,0]
	v_pk_mul_f32 v[78:79], v[78:79], v[148:149] op_sel_hi:[1,0]
	v_mov_b32_e32 v72, v76
	v_mov_b32_e32 v73, v180
	v_pk_mul_f32 v[74:75], v[74:75], v[74:75]
	v_pk_mul_f32 v[190:191], v[66:67], v[148:149] op_sel_hi:[1,0]
	v_mov_b32_e32 v66, v193
	v_mov_b32_e32 v67, v69
	v_pk_fma_f32 v[72:73], v[72:73], v[72:73], v[74:75]
	v_mov_b32_e32 v74, v78
	v_mov_b32_e32 v75, v178
	v_pk_mul_f32 v[188:189], v[70:71], v[148:149] op_sel_hi:[1,0]
	v_mov_b32_e32 v64, v192
	v_mov_b32_e32 v65, v68
	v_pk_mul_f32 v[66:67], v[66:67], v[66:67]
	v_pk_fma_f32 v[72:73], v[74:75], v[74:75], v[72:73]
	v_mov_b32_e32 v74, v79
	v_mov_b32_e32 v75, v179
	v_pk_fma_f32 v[64:65], v[64:65], v[64:65], v[66:67]
	v_mov_b32_e32 v66, v190
	v_mov_b32_e32 v67, v188
	v_pk_fma_f32 v[72:73], v[74:75], v[74:75], v[72:73]
	v_pk_fma_f32 v[64:65], v[66:67], v[66:67], v[64:65]
	v_mov_b32_e32 v66, v191
	v_mov_b32_e32 v67, v189
	v_pk_fma_f32 v[64:65], v[66:67], v[66:67], v[64:65]
	v_add_f32_e32 v66, v72, v73
	v_add_f32_e32 v65, v65, v66
	v_add_f32_e32 v72, v64, v65
	ds_bpermute_b32 v73, v176, v72
	v_pk_mul_f32 v[66:67], v[186:187], v[150:151] op_sel_hi:[1,0]
	v_pk_mul_f32 v[64:65], v[184:185], v[150:151] op_sel_hi:[1,0]
	v_pk_mul_f32 v[84:85], v[130:131], v[84:85]
	v_pk_mul_f32 v[70:71], v[128:129], v[146:147]
	s_waitcnt lgkmcnt(0)
	v_add_f32_e32 v75, v72, v73
	ds_bpermute_b32 v145, v175, v75
	v_pk_mul_f32 v[64:65], v[118:119], v[64:65]
	v_pk_mul_f32 v[66:67], v[116:117], v[66:67]
	v_cvt_pk_bf16_f32 v72, v70, v71
	v_cvt_pk_bf16_f32 v73, v84, v85
	s_waitcnt lgkmcnt(0)
	v_add_f32_e32 v75, v75, v145
	v_fmamk_f32 v75, v75, 0x3c800000, v166
	v_rsq_f32_e32 v145, v75
	v_cvt_pk_bf16_f32 v74, v66, v67
	v_cvt_pk_bf16_f32 v75, v64, v65
	v_lshl_add_u64 v[182:183], v[182:183], 0, s[100:101]
	global_store_dwordx4 v[182:183], v[72:75], off offset:64
	v_mul_f32_e32 v156, v174, v145
	v_pk_mul_f32 v[186:187], v[48:49], v[112:113] op_sel_hi:[1,0]
	v_or_b32_e32 v72, 48, v144
	v_ashrrev_i32_e32 v73, 31, v72
	v_lshlrev_b64 v[72:73], 7, v[72:73]
	v_lshl_add_u64 v[182:183], v[142:143], 0, v[72:73]
	v_lshl_add_u64 v[182:183], v[182:183], 0, v[240:241]
	v_pk_mul_f32 v[72:73], v[76:77], v[156:157] op_sel_hi:[1,0]
	v_pk_mul_f32 v[74:75], v[78:79], v[156:157] op_sel_hi:[1,0]
	v_pk_mul_f32 v[146:147], v[132:133], v[72:73]
	v_pk_mul_f32 v[78:79], v[134:135], v[74:75]
	v_pk_mul_f32 v[72:73], v[180:181], v[156:157] op_sel_hi:[1,0]
	v_pk_mul_f32 v[74:75], v[178:179], v[156:157] op_sel_hi:[1,0]
	v_pk_mul_f32 v[76:77], v[124:125], v[72:73]
	v_pk_mul_f32 v[74:75], v[126:127], v[74:75]
	v_cvt_pk_bf16_f32 v148, v146, v147
	v_cvt_pk_bf16_f32 v149, v78, v79
	v_cvt_pk_bf16_f32 v150, v76, v77
	v_cvt_pk_bf16_f32 v151, v74, v75
	global_store_dwordx4 v[182:183], v[148:151], off
	v_pk_mul_f32 v[180:181], v[52:53], v[112:113] op_sel_hi:[1,0]
	v_pk_mul_f32 v[184:185], v[50:51], v[112:113] op_sel_hi:[1,0]
	v_mov_b32_e32 v150, v61
	v_mov_b32_e32 v151, v57
	v_pk_mul_f32 v[148:149], v[58:59], v[112:113] op_sel_hi:[1,0]
	v_mov_b32_e32 v58, v60
	v_mov_b32_e32 v59, v56
	v_pk_mul_f32 v[150:151], v[150:151], v[150:151]
	v_mov_b32_e32 v50, v187
	v_mov_b32_e32 v51, v181
	v_pk_fma_f32 v[58:59], v[58:59], v[58:59], v[150:151]
	v_mov_b32_e32 v150, v62
	v_mov_b32_e32 v151, v148
	v_pk_mul_f32 v[178:179], v[54:55], v[112:113] op_sel_hi:[1,0]
	v_mov_b32_e32 v48, v186
	v_mov_b32_e32 v49, v180
	v_pk_mul_f32 v[50:51], v[50:51], v[50:51]
	v_pk_fma_f32 v[58:59], v[150:151], v[150:151], v[58:59]
	v_mov_b32_e32 v150, v63
	v_mov_b32_e32 v151, v149
	v_pk_fma_f32 v[48:49], v[48:49], v[48:49], v[50:51]
	v_mov_b32_e32 v50, v184
	v_mov_b32_e32 v51, v178
	v_pk_fma_f32 v[58:59], v[150:151], v[150:151], v[58:59]
	v_pk_fma_f32 v[48:49], v[50:51], v[50:51], v[48:49]
	v_mov_b32_e32 v50, v185
	v_mov_b32_e32 v51, v179
	v_pk_fma_f32 v[48:49], v[50:51], v[50:51], v[48:49]
	v_add_f32_e32 v50, v58, v59
	v_add_f32_e32 v49, v49, v50
	v_add_f32_e32 v52, v48, v49
	ds_bpermute_b32 v53, v176, v52
	v_pk_mul_f32 v[72:73], v[68:69], v[156:157] op_sel_hi:[1,0]
	v_pk_mul_f32 v[68:69], v[188:189], v[156:157] op_sel_hi:[1,0]
	v_pk_mul_f32 v[50:51], v[192:193], v[156:157] op_sel_hi:[1,0]
	v_pk_mul_f32 v[48:49], v[190:191], v[156:157] op_sel_hi:[1,0]
	s_waitcnt lgkmcnt(0)
; DI u32x2 pk4(f32x4 v) { u32x2 r; r.x = pk2(v[0], v[1]); r.y = pk2(v[2], v[3]); return r; }
; template <int REG>
; DI void epi_inproj(const Params& p, f32x4 (&acc)[2][2][4][2], int pm, int pn, LAS unsigned char* shm) {
;     ...
;         const int r = 128 * ai + 64 * wr + 16 * m + fr, t = t0 + r;
;         const float rs = rsr[ai][m];
;         f32x4 v[2][2]; float ss = 0.f;
; #pragma unroll
;         for (int bj = 0; bj < 2; ++bj)
; #pragma unroll
;           for (int n = 0; n < 2; ++n) { v[bj][n] = acc[ai][bj][m][n] * rs; ss += v[bj][n][0] * v[bj][n][0] + v[bj][n][1] * v[bj][n][1] + v[bj][n][2] * v[bj][n][2] + v[bj][n][3] * v[bj][n][3]; }
;         ss += __shfl_xor(ss, 16); ss += __shfl_xor(ss, 32);
;         const float rn = __builtin_amdgcn_rsqf(ss * (1.0f / 64.0f) + 1e-6f) * (isk ? 1.0f : 0.125f * 1.4426950408889634f);
;         bf16_t* dst = dstb + ((long)((b * 8 + hh) * SEQ + t)) * 64 + 8 * fq;
; #pragma unroll
;         for (int bj = 0; bj < 2; ++bj) {
;           const f32x4 o0 = v[bj][0] * rn * w4[bj][0], o1 = v[bj][1] * rn * w4[bj][1]; cs4[bj][0] += o0; cs4[bj][1] += o1;
;           const u32x2 h0 = pk4(o0), h1 = pk4(o1);
;           *(u32x4*)(dst + 32 * bj) = (u32x4){h0.x, h0.y, h1.x, h1.y};
;         }
	v_add_f32_e32 v58, v52, v53
	ds_bpermute_b32 v59, v175, v58
	v_pk_mul_f32 v[68:69], v[130:131], v[68:69]
	v_pk_mul_f32 v[72:73], v[128:129], v[72:73]
	v_pk_mul_f32 v[48:49], v[118:119], v[48:49]
	v_pk_mul_f32 v[50:51], v[116:117], v[50:51]
	s_waitcnt lgkmcnt(0)
	v_add_f32_e32 v58, v58, v59
	v_fmamk_f32 v58, v58, 0x3c800000, v166
	v_rsq_f32_e32 v58, v58
	v_cvt_pk_bf16_f32 v52, v72, v73
	v_cvt_pk_bf16_f32 v53, v68, v69
	v_cvt_pk_bf16_f32 v54, v50, v51
	v_cvt_pk_bf16_f32 v55, v48, v49
	v_lshl_add_u64 v[182:183], v[182:183], 0, s[100:101]
	global_store_dwordx4 v[182:183], v[52:55], off offset:64
	v_mul_f32_e32 v156, v174, v58
	v_pk_mul_f32 v[44:45], v[44:45], v[112:113] op_sel:[0,1]
	v_add_u32_e32 v52, 0x80, v144
	v_ashrrev_i32_e32 v53, 31, v52
	v_lshlrev_b64 v[52:53], 7, v[52:53]
	v_lshl_add_u64 v[182:183], v[142:143], 0, v[52:53]
	v_lshl_add_u64 v[182:183], v[182:183], 0, v[238:239]
	v_pk_mul_f32 v[52:53], v[60:61], v[156:157] op_sel_hi:[1,0]
	v_pk_mul_f32 v[54:55], v[62:63], v[156:157] op_sel_hi:[1,0]
	v_pk_mul_f32 v[60:61], v[132:133], v[52:53]
	v_pk_mul_f32 v[58:59], v[134:135], v[54:55]
	v_pk_mul_f32 v[52:53], v[56:57], v[156:157] op_sel_hi:[1,0]
	v_pk_mul_f32 v[54:55], v[148:149], v[156:157] op_sel_hi:[1,0]
	v_pk_mul_f32 v[56:57], v[124:125], v[52:53]
	v_pk_mul_f32 v[54:55], v[126:127], v[54:55]
	v_cvt_pk_bf16_f32 v148, v60, v61
	v_cvt_pk_bf16_f32 v149, v58, v59
	v_cvt_pk_bf16_f32 v150, v56, v57
	v_cvt_pk_bf16_f32 v151, v54, v55
	global_store_dwordx4 v[182:183], v[148:151], off
	v_pk_mul_f32 v[62:63], v[180:181], v[156:157] op_sel_hi:[1,0]
	v_pk_mul_f32 v[52:53], v[178:179], v[156:157] op_sel_hi:[1,0]
	v_pk_mul_f32 v[150:151], v[40:41], v[112:113] op_sel:[0,1]
	v_pk_mul_f32 v[46:47], v[46:47], v[112:113] op_sel:[0,1]
	v_pk_mul_f32 v[148:149], v[42:43], v[112:113] op_sel:[0,1]
	v_mov_b32_e32 v42, v45
	v_mov_b32_e32 v43, v151
	v_pk_mul_f32 v[178:179], v[38:39], v[112:113] op_sel:[0,1]
	v_pk_mul_f32 v[36:37], v[36:37], v[112:113] op_sel:[0,1]
	v_pk_mul_f32 v[180:181], v[34:35], v[112:113] op_sel:[0,1]
	v_pk_mul_f32 v[112:113], v[32:33], v[112:113] op_sel:[0,1]
	v_mov_b32_e32 v40, v44
	v_mov_b32_e32 v41, v150
	v_pk_mul_f32 v[42:43], v[42:43], v[42:43]
	v_mov_b32_e32 v34, v113
	v_mov_b32_e32 v35, v37
	v_pk_fma_f32 v[40:41], v[40:41], v[40:41], v[42:43]
	v_mov_b32_e32 v42, v46
	v_mov_b32_e32 v43, v148
	v_mov_b32_e32 v32, v112
	v_mov_b32_e32 v33, v36
	v_pk_mul_f32 v[34:35], v[34:35], v[34:35]
	v_pk_fma_f32 v[40:41], v[42:43], v[42:43], v[40:41]
	v_mov_b32_e32 v42, v47
	v_mov_b32_e32 v43, v149
	v_pk_fma_f32 v[32:33], v[32:33], v[32:33], v[34:35]
	v_mov_b32_e32 v34, v180
	v_mov_b32_e32 v35, v178
	v_pk_fma_f32 v[40:41], v[42:43], v[42:43], v[40:41]
	v_pk_fma_f32 v[32:33], v[34:35], v[34:35], v[32:33]
	v_mov_b32_e32 v34, v181
	v_mov_b32_e32 v35, v179
	v_pk_fma_f32 v[32:33], v[34:35], v[34:35], v[32:33]
	v_add_f32_e32 v34, v40, v41
	v_add_f32_e32 v33, v33, v34
	v_add_f32_e32 v40, v32, v33
	ds_bpermute_b32 v41, v176, v40
	v_pk_mul_f32 v[38:39], v[128:129], v[62:63]
	v_pk_mul_f32 v[34:35], v[186:187], v[156:157] op_sel_hi:[1,0]
	v_pk_mul_f32 v[32:33], v[184:185], v[156:157] op_sel_hi:[1,0]
	v_pk_mul_f32 v[52:53], v[130:131], v[52:53]
	s_waitcnt lgkmcnt(0)
	v_add_f32_e32 v43, v40, v41
	ds_bpermute_b32 v62, v175, v43
	v_pk_mul_f32 v[32:33], v[118:119], v[32:33]
	v_pk_mul_f32 v[34:35], v[116:117], v[34:35]
	v_cvt_pk_bf16_f32 v40, v38, v39
	v_cvt_pk_bf16_f32 v41, v52, v53
	s_waitcnt lgkmcnt(0)
	v_add_f32_e32 v43, v43, v62
	v_fmamk_f32 v43, v43, 0x3c800000, v166
	v_rsq_f32_e32 v62, v43
	v_cvt_pk_bf16_f32 v42, v34, v35
	v_cvt_pk_bf16_f32 v43, v32, v33
	v_lshl_add_u64 v[182:183], v[182:183], 0, s[100:101]
	global_store_dwordx4 v[182:183], v[40:43], off offset:64
	v_mul_f32_e32 v62, v174, v62
	v_pk_mul_f32 v[28:29], v[28:29], v[114:115] op_sel_hi:[1,0]
	v_add_u32_e32 v40, 0x90, v144
	v_ashrrev_i32_e32 v41, 31, v40
	v_lshlrev_b64 v[40:41], 7, v[40:41]
	v_lshl_add_u64 v[182:183], v[142:143], 0, v[40:41]
	v_lshl_add_u64 v[182:183], v[182:183], 0, v[240:241]
	v_pk_mul_f32 v[40:41], v[44:45], v[62:63] op_sel_hi:[1,0]
	v_pk_mul_f32 v[42:43], v[46:47], v[62:63] op_sel_hi:[1,0]
	v_pk_mul_f32 v[46:47], v[132:133], v[40:41]
	v_pk_mul_f32 v[44:45], v[134:135], v[42:43]
	v_pk_mul_f32 v[42:43], v[150:151], v[62:63] op_sel_hi:[1,0]
	v_pk_mul_f32 v[40:41], v[148:149], v[62:63] op_sel_hi:[1,0]
	v_pk_mul_f32 v[42:43], v[124:125], v[42:43]
	v_pk_mul_f32 v[40:41], v[126:127], v[40:41]
	v_cvt_pk_bf16_f32 v148, v46, v47
	v_cvt_pk_bf16_f32 v149, v44, v45
	v_cvt_pk_bf16_f32 v150, v42, v43
	v_cvt_pk_bf16_f32 v151, v40, v41
	global_store_dwordx4 v[182:183], v[148:151], off
	v_pk_mul_f32 v[20:21], v[20:21], v[114:115] op_sel_hi:[1,0]
	v_pk_mul_f32 v[188:189], v[16:17], v[114:115] op_sel_hi:[1,0]
	v_pk_mul_f32 v[148:149], v[36:37], v[62:63] op_sel_hi:[1,0]
	v_pk_mul_f32 v[36:37], v[178:179], v[62:63] op_sel_hi:[1,0]
	v_pk_mul_f32 v[178:179], v[24:25], v[114:115] op_sel_hi:[1,0]
	v_pk_mul_f32 v[150:151], v[26:27], v[114:115] op_sel_hi:[1,0]
	v_mov_b32_e32 v26, v29
	v_mov_b32_e32 v27, v179
	v_pk_mul_f32 v[30:31], v[30:31], v[114:115] op_sel_hi:[1,0]
	v_mov_b32_e32 v24, v28
	v_mov_b32_e32 v25, v178
	v_pk_mul_f32 v[26:27], v[26:27], v[26:27]
	v_pk_mul_f32 v[186:187], v[18:19], v[114:115] op_sel_hi:[1,0]
	v_mov_b32_e32 v18, v189
	v_mov_b32_e32 v19, v21
	v_pk_fma_f32 v[24:25], v[24:25], v[24:25], v[26:27]
	v_mov_b32_e32 v26, v30
	v_mov_b32_e32 v27, v150
	v_pk_mul_f32 v[184:185], v[22:23], v[114:115] op_sel_hi:[1,0]
	v_mov_b32_e32 v16, v188
	v_mov_b32_e32 v17, v20
	v_pk_mul_f32 v[18:19], v[18:19], v[18:19]
	v_pk_fma_f32 v[24:25], v[26:27], v[26:27], v[24:25]
	v_mov_b32_e32 v26, v31
	v_mov_b32_e32 v27, v151
	v_pk_fma_f32 v[16:17], v[16:17], v[16:17], v[18:19]
	v_mov_b32_e32 v18, v186
	v_mov_b32_e32 v19, v184
	v_pk_fma_f32 v[24:25], v[26:27], v[26:27], v[24:25]
	v_pk_fma_f32 v[16:17], v[18:19], v[18:19], v[16:17]
	v_mov_b32_e32 v18, v187
	v_mov_b32_e32 v19, v185
	v_pk_fma_f32 v[16:17], v[18:19], v[18:19], v[16:17]
	v_add_f32_e32 v18, v24, v25
	v_add_f32_e32 v17, v17, v18
	v_add_f32_e32 v24, v16, v17
	ds_bpermute_b32 v25, v176, v24
	v_pk_mul_f32 v[18:19], v[112:113], v[62:63] op_sel_hi:[1,0]
	v_pk_mul_f32 v[16:17], v[180:181], v[62:63] op_sel_hi:[1,0]
	v_pk_mul_f32 v[36:37], v[130:131], v[36:37]
	v_pk_mul_f32 v[22:23], v[128:129], v[148:149]
	s_waitcnt lgkmcnt(0)
; #define LAS __attribute__((address_space(3)))
; DI u32x2 pk4(f32x4 v) { u32x2 r; r.x = pk2(v[0], v[1]); r.y = pk2(v[2], v[3]); return r; }
; template <int REG>
; DI void epi_inproj(const Params& p, f32x4 (&acc)[2][2][4][2], int pm, int pn, LAS unsigned char* shm) {
;     ...
;         const int r = 128 * ai + 64 * wr + 16 * m + fr, t = t0 + r;
;         const float rs = rsr[ai][m];
;         f32x4 v[2][2]; float ss = 0.f;
; #pragma unroll
;         for (int bj = 0; bj < 2; ++bj)
; #pragma unroll
;           for (int n = 0; n < 2; ++n) { v[bj][n] = acc[ai][bj][m][n] * rs; ss += v[bj][n][0] * v[bj][n][0] + v[bj][n][1] * v[bj][n][1] + v[bj][n][2] * v[bj][n][2] + v[bj][n][3] * v[bj][n][3]; }
;         ss += __shfl_xor(ss, 16); ss += __shfl_xor(ss, 32);
;         const float rn = __builtin_amdgcn_rsqf(ss * (1.0f / 64.0f) + 1e-6f) * (isk ? 1.0f : 0.125f * 1.4426950408889634f);
;         bf16_t* dst = dstb + ((long)((b * 8 + hh) * SEQ + t)) * 64 + 8 * fq;
; #pragma unroll
;         for (int bj = 0; bj < 2; ++bj) {
;           const f32x4 o0 = v[bj][0] * rn * w4[bj][0], o1 = v[bj][1] * rn * w4[bj][1]; cs4[bj][0] += o0; cs4[bj][1] += o1;
;           const u32x2 h0 = pk4(o0), h1 = pk4(o1);
;           *(u32x4*)(dst + 32 * bj) = (u32x4){h0.x, h0.y, h1.x, h1.y};
;         }
;       }
;     if (isk) {
;       LAS float* red = (LAS float*)(shm + 131072);
; #pragma unroll
;       for (int bj = 0; bj < 2; ++bj)
; #pragma unroll
;         for (int n = 0; n < 2; ++n)
; #pragma unroll
;           for (int j = 0; j < 4; ++j) {
;             float s = cs4[bj][n][j];
;             s += __shfl_xor(s, 1); s += __shfl_xor(s, 2); s += __shfl_xor(s, 4); s += __shfl_xor(s, 8);
;             if (fr == 0) red[wr * 256 + wc * 64 + 32 * bj + 8 * fq + 4 * n + j] = s;
	v_add_f32_e32 v27, v24, v25
	ds_bpermute_b32 v62, v175, v27
	v_pk_mul_f32 v[16:17], v[118:119], v[16:17]
	v_pk_mul_f32 v[18:19], v[116:117], v[18:19]
	v_cvt_pk_bf16_f32 v24, v22, v23
	v_cvt_pk_bf16_f32 v25, v36, v37
	s_waitcnt lgkmcnt(0)
	v_add_f32_e32 v27, v27, v62
	v_fmamk_f32 v27, v27, 0x3c800000, v166
	v_rsq_f32_e32 v62, v27
	v_cvt_pk_bf16_f32 v26, v18, v19
	v_cvt_pk_bf16_f32 v27, v16, v17
	v_lshl_add_u64 v[182:183], v[182:183], 0, s[100:101]
	global_store_dwordx4 v[182:183], v[24:27], off offset:64
	v_mul_f32_e32 v112, v174, v62
	v_mov_b32_e32 v114, v115
	v_add_u32_e32 v24, 0xa0, v144
	v_ashrrev_i32_e32 v25, 31, v24
	v_lshlrev_b64 v[24:25], 7, v[24:25]
	v_lshl_add_u64 v[180:181], v[142:143], 0, v[24:25]
	v_lshl_add_u64 v[180:181], v[180:181], 0, v[238:239]
	v_pk_mul_f32 v[24:25], v[28:29], v[112:113] op_sel_hi:[1,0]
	v_pk_mul_f32 v[26:27], v[30:31], v[112:113] op_sel_hi:[1,0]
	v_pk_mul_f32 v[62:63], v[132:133], v[24:25]
	v_pk_mul_f32 v[28:29], v[134:135], v[26:27]
	v_pk_mul_f32 v[26:27], v[178:179], v[112:113] op_sel_hi:[1,0]
	v_pk_mul_f32 v[24:25], v[150:151], v[112:113] op_sel_hi:[1,0]
	v_pk_mul_f32 v[26:27], v[124:125], v[26:27]
	v_pk_mul_f32 v[24:25], v[126:127], v[24:25]
	v_cvt_pk_bf16_f32 v148, v62, v63
	v_cvt_pk_bf16_f32 v149, v28, v29
	v_cvt_pk_bf16_f32 v150, v26, v27
	v_cvt_pk_bf16_f32 v151, v24, v25
	global_store_dwordx4 v[180:181], v[148:151], off
	v_pk_mul_f32 v[12:13], v[12:13], v[114:115] op_sel_hi:[1,0]
	v_pk_mul_f32 v[30:31], v[20:21], v[112:113] op_sel_hi:[1,0]
	v_pk_mul_f32 v[150:151], v[8:9], v[114:115] op_sel_hi:[1,0]
	v_pk_mul_f32 v[20:21], v[184:185], v[112:113] op_sel_hi:[1,0]
	v_pk_mul_f32 v[148:149], v[10:11], v[114:115] op_sel_hi:[1,0]
	v_mov_b32_e32 v10, v13
	v_mov_b32_e32 v11, v151
	v_pk_mul_f32 v[182:183], v[4:5], v[114:115] op_sel_hi:[1,0]
	v_pk_mul_f32 v[184:185], v[0:1], v[114:115] op_sel_hi:[1,0]
	v_pk_mul_f32 v[14:15], v[14:15], v[114:115] op_sel_hi:[1,0]
	v_mov_b32_e32 v8, v12
	v_mov_b32_e32 v9, v150
	v_pk_mul_f32 v[10:11], v[10:11], v[10:11]
	v_mov_b32_e32 v4, v185
	v_mov_b32_e32 v5, v183
	v_pk_fma_f32 v[8:9], v[8:9], v[8:9], v[10:11]
	v_mov_b32_e32 v10, v14
	v_mov_b32_e32 v11, v148
	v_pk_mul_f32 v[178:179], v[6:7], v[114:115] op_sel_hi:[1,0]
	v_pk_mul_f32 v[2:3], v[2:3], v[114:115] op_sel_hi:[1,0]
	v_mov_b32_e32 v0, v184
	v_mov_b32_e32 v1, v182
	v_pk_mul_f32 v[4:5], v[4:5], v[4:5]
	v_pk_fma_f32 v[8:9], v[10:11], v[10:11], v[8:9]
	v_mov_b32_e32 v10, v15
	v_mov_b32_e32 v11, v149
	v_pk_fma_f32 v[0:1], v[0:1], v[0:1], v[4:5]
	v_mov_b32_e32 v4, v2
	v_mov_b32_e32 v5, v178
	v_pk_fma_f32 v[8:9], v[10:11], v[10:11], v[8:9]
	v_pk_fma_f32 v[0:1], v[4:5], v[4:5], v[0:1]
	v_mov_b32_e32 v4, v3
	v_mov_b32_e32 v5, v179
	v_pk_fma_f32 v[0:1], v[4:5], v[4:5], v[0:1]
	v_add_f32_e32 v4, v8, v9
	v_add_f32_e32 v1, v1, v4
	v_add_f32_e32 v6, v0, v1
	ds_bpermute_b32 v7, v176, v6
	v_pk_mul_f32 v[10:11], v[128:129], v[30:31]
	v_pk_mul_f32 v[4:5], v[188:189], v[112:113] op_sel_hi:[1,0]
	v_pk_mul_f32 v[0:1], v[186:187], v[112:113] op_sel_hi:[1,0]
	v_pk_mul_f32 v[20:21], v[130:131], v[20:21]
	s_waitcnt lgkmcnt(0)
	v_add_f32_e32 v9, v6, v7
	ds_bpermute_b32 v30, v175, v9
	v_pk_mul_f32 v[0:1], v[118:119], v[0:1]
	v_pk_mul_f32 v[4:5], v[116:117], v[4:5]
	v_cvt_pk_bf16_f32 v6, v10, v11
	v_cvt_pk_bf16_f32 v7, v20, v21
	s_waitcnt lgkmcnt(0)
	v_add_f32_e32 v9, v9, v30
	v_fmamk_f32 v9, v9, 0x3c800000, v166
	v_rsq_f32_e32 v30, v9
	v_cvt_pk_bf16_f32 v8, v4, v5
	v_cvt_pk_bf16_f32 v9, v0, v1
	v_lshl_add_u64 v[180:181], v[180:181], 0, s[100:101]
	global_store_dwordx4 v[180:181], v[6:9], off offset:64
	v_mul_f32_e32 v156, v174, v30
	v_pk_mul_f32 v[2:3], v[2:3], v[156:157] op_sel_hi:[1,0]
	v_add_u32_e32 v6, 0xb0, v144
	v_ashrrev_i32_e32 v7, 31, v6
	v_lshlrev_b64 v[6:7], 7, v[6:7]
	v_lshl_add_u64 v[142:143], v[142:143], 0, v[6:7]
	v_lshl_add_u64 v[142:143], v[142:143], 0, v[240:241]
	v_pk_mul_f32 v[6:7], v[12:13], v[156:157] op_sel_hi:[1,0]
	v_pk_mul_f32 v[8:9], v[14:15], v[156:157] op_sel_hi:[1,0]
	v_pk_mul_f32 v[114:115], v[132:133], v[6:7]
	v_pk_mul_f32 v[112:113], v[134:135], v[8:9]
	v_pk_mul_f32 v[6:7], v[150:151], v[156:157] op_sel_hi:[1,0]
	v_pk_mul_f32 v[8:9], v[148:149], v[156:157] op_sel_hi:[1,0]
	v_pk_mul_f32 v[30:31], v[124:125], v[6:7]
	v_pk_mul_f32 v[14:15], v[126:127], v[8:9]
	v_cvt_pk_bf16_f32 v6, v114, v115
	v_cvt_pk_bf16_f32 v7, v112, v113
	v_cvt_pk_bf16_f32 v8, v30, v31
	v_cvt_pk_bf16_f32 v9, v14, v15
	global_store_dwordx4 v[142:143], v[6:9], off
	v_pk_mul_f32 v[2:3], v[118:119], v[2:3]
	s_nop 0
	v_pk_mul_f32 v[6:7], v[182:183], v[156:157] op_sel_hi:[1,0]
	v_pk_mul_f32 v[8:9], v[178:179], v[156:157] op_sel_hi:[1,0]
	v_pk_mul_f32 v[12:13], v[128:129], v[6:7]
	v_pk_mul_f32 v[6:7], v[184:185], v[156:157] op_sel_hi:[1,0]
	v_pk_mul_f32 v[8:9], v[130:131], v[8:9]
	v_pk_mul_f32 v[6:7], v[116:117], v[6:7]
	v_cvt_pk_bf16_f32 v116, v12, v13
	v_cvt_pk_bf16_f32 v117, v8, v9
	v_cvt_pk_bf16_f32 v118, v6, v7
	v_cvt_pk_bf16_f32 v119, v2, v3
	v_lshl_add_u64 v[142:143], v[142:143], 0, s[100:101]
	global_store_dwordx4 v[142:143], v[116:119], off offset:64
	s_cbranch_scc1 .LBB0_471
	s_nop 0
	v_pk_add_f32 v[116:117], v[140:141], 0 op_sel_hi:[1,0]
	s_nop 0
	v_pk_add_f32 v[110:111], v[116:117], v[110:111]
	s_nop 0
	v_pk_add_f32 v[94:95], v[110:111], v[94:95]
	v_lshlrev_b32_e32 v110, 8, v173
	v_pk_add_f32 v[94:95], v[94:95], v[146:147]
	s_nop 0
	v_pk_add_f32 v[60:61], v[94:95], v[60:61]
	s_nop 0
	v_pk_add_f32 v[46:47], v[60:61], v[46:47]
	v_xor_b32_e32 v60, 1, v165
	v_cmp_lt_i32_e32 vcc, v60, v172
	v_pk_add_f32 v[46:47], v[46:47], v[62:63]
	v_xor_b32_e32 v61, 2, v165
	v_cndmask_b32_e32 v60, v165, v60, vcc
	v_pk_add_f32 v[46:47], v[46:47], v[114:115]
	v_lshlrev_b32_e32 v60, 2, v60
	ds_bpermute_b32 v62, v60, v46
	v_cmp_lt_i32_e32 vcc, v61, v172
	v_xor_b32_e32 v63, 4, v165
	s_waitcnt lgkmcnt(0)
	v_add_f32_e32 v62, v46, v62
	v_cndmask_b32_e32 v61, v165, v61, vcc
	v_lshlrev_b32_e32 v61, 2, v61
	ds_bpermute_b32 v94, v61, v62
	v_cmp_lt_i32_e32 vcc, v63, v172
	s_waitcnt lgkmcnt(0)
	v_add_f32_e32 v94, v62, v94
	v_cndmask_b32_e32 v46, v165, v63, vcc
	v_lshlrev_b32_e32 v46, 2, v46
	ds_bpermute_b32 v95, v46, v94
	v_xor_b32_e32 v63, 8, v165
	v_cmp_lt_i32_e32 vcc, v63, v172
	s_waitcnt lgkmcnt(0)
	v_add_f32_e32 v94, v94, v95
	v_cndmask_b32_e32 v62, v165, v63, vcc
	v_lshlrev_b32_e32 v62, 2, v62
	ds_bpermute_b32 v95, v62, v94
	v_and_b32_e32 v63, 0x3fffff00, v168
	v_lshlrev_b32_e32 v63, 2, v63
	v_add3_u32 v63, s77, v63, v110
	v_cmp_eq_u32_e32 vcc, 0, v170
	v_add_u32_e32 v63, v63, v171
	s_and_saveexec_b64 s[22:23], vcc
	s_cbranch_execz .LBB0_438
	s_waitcnt lgkmcnt(0)
	v_add_f32_e32 v94, v94, v95
	ds_write_b32 v63, v94

;     ...
;         const int sw = wid & 3, prow = (fr >> 2) * 8 + (fr & 3);
;         bf16x8 kf[4][2], kn[4][2];
; #pragma unroll
;         for (int a = 0; a < 4; ++a) { kf[a][0] = (bf16x8){0, 0, 0, 0, 0, 0, 0, 0}; kf[a][1] = kf[a][0]; }
;         int stepc = 0;
;         auto ssteps = [&](const int j, auto ownc) {
;           constexpr bool own = decltype(ownc)::value;
;           const int n = j < 0 ? 0 : (own ? 256 : cnt[j]), ntile = (n + 15) >> 4;
;           for (int s0 = 0; s0 < ntile; s0 += 2, ++stepc) {
;             LAS unsigned char* pbuf = Pb + (stepc & 1) * 16384;
;             if (!(mode & 4))
; #pragma unroll
;             for (int tt = 0; tt < 2; ++tt) {
;               const int tile = s0 + tt;
;               if (tile < ntile) {
;                 const int rem = n - tile * 16;
;                 const int qidx = own ? tile * 16 + fr : (int)list[j * 256 + tile * 16 + (fr < rem ? fr : 0)];
;                 const bf16x8 q0 = *(const LAS bf16x8*)(Qs + qidx * MO_QS + fq * 16), q1 = *(const LAS bf16x8*)(Qs + qidx * MO_QS + 64 + fq * 16);
; #pragma unroll
;                 for (int g = 0; g < 2; ++g) {
;                   f32x4 sv[2];
; #pragma unroll
;                   for (int par = 0; par < 2; ++par) { sv[par] = MFMA16(kf[g * 2 + par][0], q0, ((f32x4){0.f, 0.f, 0.f, 0.f})); sv[par] = MFMA16(kf[g * 2 + par][1], q1, sv[par]); }
;                   float pv[2][4];
; #pragma unroll
;                   for (int par = 0; par < 2; ++par)
; #pragma unroll
;                     for (int i = 0; i < 4; ++i) {
;                       float pe = fast_exp2(sv[par][i] - c2);
;                       if (own) { const int key = 64 * sw + 32 * g + fq * 8 + 4 * par + i; if (key > qidx) pe = 0.f; }
;                       pv[par][i] = pe;
;                     }
;                   u32x4 pw; pw.x = pk2(pv[0][0], pv[0][1]); pw.y = pk2(pv[0][2], pv[0][3]); pw.z = pk2(pv[1][0], pv[1][1]); pw.w = pk2(pv[1][2], pv[1][3]);
;                   *(LAS u32x4*)(pbuf + tt * 8192 + (2 * sw + g) * 1024 + lane * 16) = pw;
;                 }
;               }
;             }
;             MO_BARRIER;
;           }
;         };
;         for (int j = -1; j < blk; ++j) {
;           {
;             const bf16_t* kp = Mk + (krow0 + (j + 1) * 256 + 64 * sw + prow) * 64 + fq * 8;
; #pragma unroll
;             for (int g = 0; g < 2; ++g)
; #pragma unroll
.LBB0_651:
	s_and_b64 vcc, exec, s[16:17]
	s_cbranch_vccz .LBB0_542
	s_cmp_lt_i32 s18, 0
	s_mov_b32 s15, 0
	s_cbranch_scc1 .LBB0_664
	s_waitcnt vmcnt(15)
	v_mov_b32_e32 v34, 0
	s_waitcnt vmcnt(8)
	v_mov_b32_e32 v67, s51
	v_or_b32_e32 v66, s50, v192
	s_lshl_b64 s[98:99], s[50:51], 7
	s_add_u32 s98, s98, s26
	s_addc_u32 s99, s99, s27
	s_add_u32 s98, s98, 0x12300000
	s_addc_u32 s99, s99, 0
	v_and_b32_e32 v112, 63, v184
	v_lshlrev_b32_e32 v112, 4, v112
	v_bfe_u32 v113, v184, 6, 2
	v_lshl_or_b32 v112, v113, 13, v112
	v_mov_b32_e32 v113, 0
	v_lshl_add_u64 v[112:113], s[98:99], 0, v[112:113]

;     ...
;         for (int j = -1; j < blk; ++j) {
;           {
;             const bf16_t* kp = Mk + (krow0 + (j + 1) * 256 + 64 * sw + prow) * 64 + fq * 8;
	s_mov_b32 s19, -1
	s_mov_b32 s14, s76
	v_mov_b32_e32 v35, v34
	s_waitcnt vmcnt(7)
	v_mov_b32_e32 v36, v34
	v_mov_b32_e32 v37, v34
	v_mov_b32_e32 v38, v34
	v_mov_b32_e32 v39, v34
	v_mov_b32_e32 v40, v34
	v_mov_b32_e32 v41, v34
	v_mov_b32_e32 v42, v34
	v_mov_b32_e32 v43, v34
	v_mov_b32_e32 v44, v34
	v_mov_b32_e32 v45, v34
	v_mov_b32_e32 v46, v34
	v_mov_b32_e32 v47, v34
	v_mov_b32_e32 v48, v34
	v_mov_b32_e32 v49, v34
	v_mov_b32_e32 v50, v34
	v_mov_b32_e32 v51, v34
	v_mov_b32_e32 v52, v34
	v_mov_b32_e32 v53, v34
	v_mov_b32_e32 v54, v34
	v_mov_b32_e32 v55, v34
	v_mov_b32_e32 v56, v34
	v_mov_b32_e32 v57, v34
	v_mov_b32_e32 v58, v34
	v_mov_b32_e32 v59, v34
	v_mov_b32_e32 v60, v34
	v_mov_b32_e32 v61, v34
	v_mov_b32_e32 v62, v34
	v_mov_b32_e32 v63, v34
	v_mov_b32_e32 v64, v34
	v_mov_b32_e32 v65, v34
.LBB0_654:
	s_add_i32 s16, s19, 1
	s_lshl_b32 s22, s16, 15

;     ...
;             const bf16_t* kp = Mk + (krow0 + (j + 1) * 256 + 64 * sw + prow) * 64 + fq * 8;
	s_ashr_i32 s23, s22, 31
	v_lshl_add_u64 v[2:3], v[112:113], 0, s[22:23]

;     ...
;           const int n = j < 0 ? 0 : (own ? 256 : cnt[j]), ntile = (n + 15) >> 4;
;     ...
;             const bf16_t* kp = Mk + (krow0 + (j + 1) * 256 + 64 * sw + prow) * 64 + fq * 8;
; #pragma unroll
;             for (int g = 0; g < 2; ++g)
; #pragma unroll
;               for (int par = 0; par < 2; ++par) { kn[g * 2 + par][0] = *(const bf16x8*)(kp + (32 * g + 4 * par) * 64); kn[g * 2 + par][1] = *(const bf16x8*)(kp + (32 * g + 4 * par) * 64 + 32); }
	global_load_dwordx4 v[30:33], v[2:3], off
	global_load_dwordx4 v[26:29], v[2:3], off offset:1024
	global_load_dwordx4 v[22:25], v[2:3], off offset:2048
	global_load_dwordx4 v[18:21], v[2:3], off offset:3072
	v_add_co_u32_e32 v2, vcc, 0x1000, v2
	s_cmp_lt_i32 s19, 0
	s_nop 0
	v_addc_co_u32_e32 v3, vcc, 0, v3, vcc
	global_load_dwordx4 v[14:17], v[2:3], off
	global_load_dwordx4 v[10:13], v[2:3], off offset:1024
	global_load_dwordx4 v[6:9], v[2:3], off offset:2048
	s_nop 0
	global_load_dwordx4 v[2:5], v[2:3], off offset:3072
	s_mov_b32 s17, 0
	s_cbranch_scc1 .LBB0_656
	s_lshl_b32 s17, s19, 2
	s_add_i32 s17, s17, 0
	s_add_i32 s17, s17, 0x10400
	v_mov_b32_e32 v1, s17
	ds_read_b32 v1, v1
	s_waitcnt lgkmcnt(0)
	v_readfirstlane_b32 s17, v1
